# v21 = v19 + dead-code removal of leftover RNE bit-trick chains in the attention KV loops (51 VALU per iteration)
# speedup vs baseline: 1.0202x; 1.0057x over previous
.LBB0_704:
	s_waitcnt lgkmcnt(0)
	s_barrier
	s_waitcnt vmcnt(0)
	ds_write_b128 v165, v[224:227]
	ds_write_b128 v166, v[228:231]
	ds_write_b128 v167, v[232:235]
	ds_write_b128 v168, v[236:239] offset:13312
	ds_write_b128 v169, v[240:243] offset:13312
	s_waitcnt lgkmcnt(0)
	s_barrier
	ds_read_b128 v[32:35], v164
	ds_read_b128 v[88:91], v164 offset:32
	v_lshl_add_u64 v[112:113], s[8:9], 0, v[138:139]
	v_lshl_add_u64 v[148:149], s[8:9], 0, v[136:137]
	v_lshl_add_u64 v[114:115], s[8:9], 0, v[134:135]
	v_lshl_add_u64 v[142:143], s[8:9], 0, v[132:133]
	v_lshl_add_u64 v[140:141], s[8:9], 0, v[130:131]
	v_lshl_add_u64 v[144:145], s[8:9], 0, v[128:129]
	v_lshl_add_u64 v[146:147], s[8:9], 0, v[126:127]
	v_cndmask_b32_e32 v113, v149, v113, vcc
	v_cndmask_b32_e32 v112, v148, v112, vcc
	v_cndmask_b32_e64 v115, v143, v115, s[4:5]
	v_cndmask_b32_e64 v114, v142, v114, s[4:5]
	v_lshl_add_u64 v[150:151], s[8:9], 0, v[124:125]
	v_cndmask_b32_e64 v145, v145, v141, s[6:7]
	v_cndmask_b32_e64 v144, v144, v140, s[6:7]
	global_load_dwordx4 v[236:239], v[146:147], off
	global_load_dwordx4 v[240:243], v[150:151], off
	global_load_dwordx4 v[224:227], v[112:113], off
	global_load_dwordx4 v[228:231], v[114:115], off
	global_load_dwordx4 v[232:235], v[144:145], off
	s_waitcnt lgkmcnt(1)
	v_mfma_f32_32x32x16_bf16 v[32:47], v[32:35], v[84:87], 0
	ds_read_b128 v[48:51], v164 offset:6656
	ds_read_b128 v[92:95], v164 offset:6688
	v_mov_b32_e32 v171, v105
	v_mov_b32_e32 v170, v104
	s_waitcnt lgkmcnt(1)
	v_mfma_f32_32x32x16_bf16 v[48:63], v[48:51], v[84:87], 0
	v_mfma_f32_32x32x16_bf16 v[32:47], v[88:91], v[80:83], v[32:47]
	ds_read_b128 v[88:91], v164 offset:64
	v_add_u32_e32 v172, v122, v163
	v_add_u32_e32 v143, 0x3000, v172
	v_add_u32_e32 v173, v122, v116
	s_waitcnt lgkmcnt(1)
	v_mfma_f32_32x32x16_bf16 v[48:63], v[92:95], v[80:83], v[48:63]
	ds_read_b128 v[100:103], v164 offset:96
	ds_read_b128 v[92:95], v164 offset:6720
	ds_read_b128 v[96:99], v164 offset:6752
	v_add_u32_e32 v174, v162, v163
	v_add_u32_e32 v175, v162, v116
	v_add_u32_e32 v142, 0x3000, v173
	v_add_u32_e32 v141, 0x3000, v174
	v_add_u32_e32 v140, 0x3000, v175
	s_waitcnt lgkmcnt(3)
	v_mfma_f32_32x32x16_bf16 v[32:47], v[88:91], v[76:79], v[32:47]
	s_add_i32 s0, s0, -1
	v_lshl_add_u64 v[124:125], v[124:125], 0, s[42:43]
	v_lshl_add_u64 v[126:127], v[126:127], 0, s[42:43]
	v_lshl_add_u64 v[128:129], v[128:129], 0, s[44:45]
	v_lshl_add_u64 v[130:131], v[130:131], 0, s[46:47]
	v_lshl_add_u64 v[132:133], v[132:133], 0, s[44:45]
	v_lshl_add_u64 v[134:135], v[134:135], 0, s[46:47]
	s_waitcnt lgkmcnt(1)
	v_mfma_f32_32x32x16_bf16 v[48:63], v[92:95], v[76:79], v[48:63]
	ds_read_b128 v[88:91], v164 offset:128
	ds_read_b128 v[104:107], v164 offset:160
	ds_read_b128 v[92:95], v164 offset:6784
	ds_read_b128 v[108:111], v164 offset:6816
	v_lshl_add_u64 v[136:137], v[136:137], 0, s[44:45]
	v_lshl_add_u64 v[138:139], v[138:139], 0, s[46:47]
	s_cmp_lg_u32 s0, 0
	v_mfma_f32_32x32x16_bf16 v[32:47], v[100:103], v[72:75], v[32:47]
	s_waitcnt lgkmcnt(4)
	v_mfma_f32_32x32x16_bf16 v[48:63], v[96:99], v[72:75], v[48:63]
	s_waitcnt lgkmcnt(0)
	v_mfma_f32_32x32x16_bf16 v[32:47], v[88:91], v[68:71], v[32:47]
	v_mfma_f32_32x32x16_bf16 v[48:63], v[92:95], v[68:71], v[48:63]
	s_nop 0
	ds_read2_b64 v[144:147], v143 offset0:128 offset1:130
	ds_read2_b64 v[148:151], v143 offset0:132 offset1:134
	ds_read2_b64 v[172:175], v142 offset0:128 offset1:130
	ds_read2_b64 v[176:179], v142 offset0:132 offset1:134
	ds_read2_b64 v[180:183], v143 offset0:136 offset1:138
	ds_read2_b64 v[184:187], v142 offset0:136 offset1:138
	ds_read2_b64 v[188:191], v141 offset0:140 offset1:142
	ds_read2_b64 v[192:195], v140 offset0:140 offset1:142
	v_mfma_f32_32x32x16_bf16 v[32:47], v[104:107], v[64:67], v[32:47]
	v_mfma_f32_32x32x16_bf16 v[48:63], v[108:111], v[64:67], v[48:63]
	s_nop 10
	v_max_f32_e32 v104, v33, v33
	v_max_f32_e32 v105, v32, v32
	v_max_f32_e32 v104, v105, v104
	v_max3_f32 v104, v104, v34, v35
	v_max3_f32 v104, v104, v36, v37
	v_max3_f32 v104, v104, v38, v39
	v_max3_f32 v104, v104, v40, v41
	v_max3_f32 v104, v104, v42, v43
	v_max3_f32 v104, v104, v44, v45
	v_max3_f32 v104, v104, v46, v47
	v_max3_f32 v104, v104, v48, v49
	v_max3_f32 v104, v104, v50, v51
	v_max3_f32 v104, v104, v52, v53
	v_max3_f32 v104, v104, v54, v55
	v_max3_f32 v104, v104, v56, v57
	v_max3_f32 v104, v104, v58, v59
	v_max3_f32 v104, v104, v60, v61
	v_max3_f32 v104, v104, v62, v63
	ds_bpermute_b32 v105, v123, v104
	s_waitcnt lgkmcnt(0)
	v_max3_f32 v105, v171, v104, v105
	v_sub_f32_e32 v104, v171, v105
	v_sub_f32_e32 v32, v32, v105
	v_sub_f32_e32 v33, v33, v105
	v_sub_f32_e32 v34, v34, v105
	v_sub_f32_e32 v35, v35, v105
	v_sub_f32_e32 v36, v36, v105
	v_sub_f32_e32 v37, v37, v105
	v_sub_f32_e32 v38, v38, v105
	v_sub_f32_e32 v39, v39, v105
	v_sub_f32_e32 v106, v42, v105
	v_exp_f32_e32 v42, v104
	v_exp_f32_e32 v32, v32
	v_exp_f32_e32 v33, v33
	s_nop 0
	v_cvt_pk_bf16_f32 v244, v32, v33
	v_exp_f32_e32 v104, v34
	v_exp_f32_e32 v107, v35
	v_exp_f32_e32 v108, v36
	v_exp_f32_e32 v109, v37
	v_exp_f32_e32 v110, v38
	v_exp_f32_e32 v111, v39
	v_sub_f32_e32 v43, v43, v105
	v_sub_f32_e32 v40, v40, v105
	v_sub_f32_e32 v41, v41, v105
	v_exp_f32_e32 v43, v43
	v_exp_f32_e32 v171, v40
	v_exp_f32_e32 v196, v41
	v_add_f32_e32 v34, 0, v32
	v_add_f32_e32 v222, v33, v34
	v_sub_f32_e32 v44, v44, v105
	v_sub_f32_e32 v45, v45, v105
	v_sub_f32_e32 v46, v46, v105
	v_pk_mul_f32 v[30:31], v[30:31], v[42:43] op_sel_hi:[1,0]
	v_pk_mul_f32 v[28:29], v[28:29], v[42:43] op_sel_hi:[1,0]
	v_pk_mul_f32 v[26:27], v[26:27], v[42:43] op_sel_hi:[1,0]
	v_pk_mul_f32 v[24:25], v[24:25], v[42:43] op_sel_hi:[1,0]
	v_pk_mul_f32 v[22:23], v[22:23], v[42:43] op_sel_hi:[1,0]
	v_pk_mul_f32 v[20:21], v[20:21], v[42:43] op_sel_hi:[1,0]
	v_pk_mul_f32 v[18:19], v[18:19], v[42:43] op_sel_hi:[1,0]
	v_pk_mul_f32 v[16:17], v[16:17], v[42:43] op_sel_hi:[1,0]
	v_pk_mul_f32 v[14:15], v[14:15], v[42:43] op_sel_hi:[1,0]
	v_pk_mul_f32 v[12:13], v[12:13], v[42:43] op_sel_hi:[1,0]
	v_pk_mul_f32 v[10:11], v[10:11], v[42:43] op_sel_hi:[1,0]
	v_pk_mul_f32 v[8:9], v[8:9], v[42:43] op_sel_hi:[1,0]
	v_pk_mul_f32 v[6:7], v[6:7], v[42:43] op_sel_hi:[1,0]
	v_pk_mul_f32 v[4:5], v[4:5], v[42:43] op_sel_hi:[1,0]
	v_pk_mul_f32 v[2:3], v[2:3], v[42:43] op_sel_hi:[1,0]
	v_pk_mul_f32 v[0:1], v[0:1], v[42:43] op_sel_hi:[1,0]
	v_cvt_pk_bf16_f32 v35, v110, v111
	v_cvt_pk_bf16_f32 v34, v108, v109
	v_cvt_pk_bf16_f32 v33, v104, v107
	v_mov_b32_e32 v32, v244
	v_sub_f32_e32 v47, v47, v105
	v_exp_f32_e32 v106, v106
	v_exp_f32_e32 v44, v44
	v_exp_f32_e32 v45, v45
	v_exp_f32_e32 v46, v46
	v_mfma_f32_32x32x16_bf16 v[16:31], v[144:147], v[32:35], v[16:31]
	v_exp_f32_e32 v47, v47
	v_mfma_f32_32x32x16_bf16 v[0:15], v[172:175], v[32:35], v[0:15]
	v_add_f32_e32 v37, v104, v222
	v_cvt_pk_bf16_f32 v35, v46, v47
	v_cvt_pk_bf16_f32 v34, v44, v45
	v_cvt_pk_bf16_f32 v33, v106, v43
	v_cvt_pk_bf16_f32 v32, v171, v196
	v_add_f32_e32 v104, v107, v37
	v_sub_f32_e32 v48, v48, v105
	v_mfma_f32_32x32x16_bf16 v[16:31], v[148:151], v[32:35], v[16:31]
	v_sub_f32_e32 v49, v49, v105
	v_sub_f32_e32 v50, v50, v105
	v_sub_f32_e32 v51, v51, v105
	v_sub_f32_e32 v52, v52, v105
	v_sub_f32_e32 v53, v53, v105
	v_sub_f32_e32 v54, v54, v105
	v_sub_f32_e32 v55, v55, v105
	v_mfma_f32_32x32x16_bf16 v[0:15], v[176:179], v[32:35], v[0:15]
	v_add_f32_e32 v32, v108, v104
	v_add_f32_e32 v32, v109, v32
	v_add_f32_e32 v32, v110, v32
	v_add_f32_e32 v32, v111, v32
	v_add_f32_e32 v32, v171, v32
	v_sub_f32_e32 v56, v56, v105
	v_exp_f32_e32 v48, v48
	v_exp_f32_e32 v49, v49
	v_exp_f32_e32 v50, v50
	v_exp_f32_e32 v51, v51
	v_exp_f32_e32 v52, v52
	v_exp_f32_e32 v53, v53
	v_exp_f32_e32 v54, v54
	v_add_f32_e32 v32, v196, v32
	v_exp_f32_e32 v55, v55
	v_exp_f32_e32 v56, v56
	v_add_f32_e32 v32, v106, v32
	v_add_f32_e32 v32, v43, v32
	v_add_f32_e32 v32, v44, v32
	v_add_f32_e32 v32, v45, v32
	v_add_f32_e32 v32, v46, v32
	v_add_f32_e32 v32, v47, v32
	v_sub_f32_e32 v57, v57, v105
	v_sub_f32_e32 v58, v58, v105
	v_sub_f32_e32 v59, v59, v105
	v_sub_f32_e32 v60, v60, v105
	v_sub_f32_e32 v61, v61, v105
	v_sub_f32_e32 v62, v62, v105
	v_cvt_pk_bf16_f32 v37, v54, v55
	v_cvt_pk_bf16_f32 v36, v52, v53
	v_cvt_pk_bf16_f32 v35, v50, v51
	v_cvt_pk_bf16_f32 v34, v48, v49
	v_add_f32_e32 v32, v48, v32
	v_sub_f32_e32 v63, v63, v105
	v_exp_f32_e32 v57, v57
	v_exp_f32_e32 v58, v58
	v_exp_f32_e32 v59, v59
	v_exp_f32_e32 v60, v60
	v_exp_f32_e32 v61, v61
	v_exp_f32_e32 v62, v62
	v_mfma_f32_32x32x16_bf16 v[16:31], v[180:183], v[34:37], v[16:31]
	v_add_f32_e32 v32, v49, v32
	v_exp_f32_e32 v63, v63
	v_add_f32_e32 v32, v50, v32
	v_add_f32_e32 v32, v51, v32
	v_add_f32_e32 v32, v52, v32
	v_mfma_f32_32x32x16_bf16 v[0:15], v[184:187], v[34:37], v[0:15]
	v_add_f32_e32 v32, v53, v32
	v_add_f32_e32 v32, v54, v32
	v_add_f32_e32 v32, v55, v32
	v_cvt_pk_bf16_f32 v41, v62, v63
	v_cvt_pk_bf16_f32 v40, v60, v61
	v_cvt_pk_bf16_f32 v39, v58, v59
	v_cvt_pk_bf16_f32 v38, v56, v57
	v_add_f32_e32 v32, v56, v32
	v_add_f32_e32 v32, v57, v32
	v_mfma_f32_32x32x16_bf16 v[16:31], v[188:191], v[38:41], v[16:31]
	v_add_f32_e32 v32, v58, v32
	v_add_f32_e32 v32, v59, v32
	v_add_f32_e32 v32, v60, v32
	v_add_f32_e32 v32, v61, v32
	v_add_f32_e32 v32, v62, v32
	v_add_f32_e32 v104, v63, v32
	v_fmac_f32_e32 v104, v170, v42
	v_mfma_f32_32x32x16_bf16 v[0:15], v[192:195], v[38:41], v[0:15]
	s_cbranch_scc1 .LBB0_704
	s_barrier
	s_waitcnt vmcnt(0)
	ds_write_b128 v165, v[224:227]
	ds_write_b128 v166, v[228:231]
	ds_write_b128 v167, v[232:235]
	ds_write_b128 v168, v[236:239] offset:13312
	ds_write_b128 v169, v[240:243] offset:13312
	s_waitcnt lgkmcnt(0)
	s_barrier
	ds_read_b128 v[32:35], v164
	ds_read_b128 v[36:39], v164 offset:32
	s_waitcnt lgkmcnt(1)
	v_mfma_f32_32x32x16_bf16 v[48:63], v[32:35], v[84:87], 0
	s_waitcnt lgkmcnt(0)
	v_mfma_f32_32x32x16_bf16 v[48:63], v[36:39], v[80:83], v[48:63]
	ds_read_b128 v[32:35], v164 offset:64
	ds_read_b128 v[36:39], v164 offset:96
	s_waitcnt lgkmcnt(1)
	v_mfma_f32_32x32x16_bf16 v[48:63], v[32:35], v[76:79], v[48:63]
	s_waitcnt lgkmcnt(0)
	v_mfma_f32_32x32x16_bf16 v[48:63], v[36:39], v[72:75], v[48:63]
	ds_read_b128 v[32:35], v164 offset:128
	ds_read_b128 v[36:39], v164 offset:160
	s_waitcnt lgkmcnt(1)
	v_mfma_f32_32x32x16_bf16 v[48:63], v[32:35], v[68:71], v[48:63]
	ds_read_b128 v[32:35], v164 offset:6656
	ds_read_b128 v[88:91], v164 offset:6688
	s_waitcnt lgkmcnt(2)
	v_mfma_f32_32x32x16_bf16 v[48:63], v[36:39], v[64:67], v[48:63]
	s_waitcnt lgkmcnt(1)
	v_mfma_f32_32x32x16_bf16 v[32:47], v[32:35], v[84:87], 0
	s_waitcnt lgkmcnt(0)
	v_mfma_f32_32x32x16_bf16 v[32:47], v[88:91], v[80:83], v[32:47]
	ds_read_b128 v[80:83], v164 offset:6720
	ds_read_b128 v[84:87], v164 offset:6752
	s_waitcnt lgkmcnt(1)
	v_mfma_f32_32x32x16_bf16 v[32:47], v[80:83], v[76:79], v[32:47]
	s_nop 3
	v_max_f32_e32 v80, v49, v49
	v_max_f32_e32 v81, v48, v48
	v_max_f32_e32 v80, v81, v80
	s_waitcnt lgkmcnt(0)
	v_mfma_f32_32x32x16_bf16 v[32:47], v[84:87], v[72:75], v[32:47]
	ds_read_b128 v[72:75], v164 offset:6784
	ds_read_b128 v[76:79], v164 offset:6816
	s_waitcnt lgkmcnt(1)
	v_mfma_f32_32x32x16_bf16 v[32:47], v[72:75], v[68:71], v[32:47]
	v_max3_f32 v68, v80, v50, v51
	v_max3_f32 v68, v68, v52, v53
	v_max3_f32 v68, v68, v54, v55
	v_max3_f32 v68, v68, v56, v57
	v_max3_f32 v68, v68, v58, v59
	v_max3_f32 v68, v68, v60, v61
	v_max3_f32 v68, v68, v62, v63
	s_waitcnt lgkmcnt(0)
	v_mfma_f32_32x32x16_bf16 v[32:47], v[76:79], v[64:67], v[32:47]
	s_nop 11
	v_max3_f32 v64, v68, v32, v33
	v_max3_f32 v64, v64, v34, v35
	v_max3_f32 v64, v64, v36, v37
	v_max3_f32 v64, v64, v38, v39
	v_max3_f32 v64, v64, v40, v41
	v_max3_f32 v64, v64, v42, v43
	v_max3_f32 v64, v64, v44, v45
	v_max3_f32 v64, v64, v46, v47
	ds_bpermute_b32 v65, v123, v64
	s_waitcnt lgkmcnt(0)
	v_max3_f32 v65, v105, v64, v65
	v_sub_f32_e32 v32, v32, v65
	v_exp_f32_e32 v66, v32
	v_sub_f32_e32 v32, v33, v65
	v_exp_f32_e32 v67, v32
	v_sub_f32_e32 v32, v34, v65
	v_exp_f32_e32 v68, v32
	v_sub_f32_e32 v32, v35, v65
	v_exp_f32_e32 v69, v32
	v_sub_f32_e32 v32, v36, v65
	v_exp_f32_e32 v70, v32
	v_sub_f32_e32 v32, v37, v65
	v_exp_f32_e32 v71, v32
	v_sub_f32_e32 v32, v38, v65
	v_exp_f32_e32 v72, v32
	v_sub_f32_e32 v32, v39, v65
	v_exp_f32_e32 v73, v32
	v_sub_f32_e32 v32, v40, v65
	v_exp_f32_e32 v74, v32
	v_sub_f32_e32 v32, v41, v65
	v_exp_f32_e32 v75, v32
	v_sub_f32_e32 v32, v42, v65
	v_sub_f32_e32 v48, v48, v65
	v_exp_f32_e32 v76, v32
	v_sub_f32_e32 v32, v43, v65
	v_exp_f32_e32 v48, v48
	v_sub_f32_e32 v49, v49, v65
	v_exp_f32_e32 v77, v32
	v_sub_f32_e32 v32, v44, v65
	v_exp_f32_e32 v49, v49
	v_sub_f32_e32 v50, v50, v65
	v_sub_f32_e32 v55, v55, v65
	v_exp_f32_e32 v78, v32
	v_sub_f32_e32 v32, v45, v65
	v_exp_f32_e32 v50, v50
	v_sub_f32_e32 v51, v51, v65
	v_sub_f32_e32 v53, v53, v65
	v_exp_f32_e32 v55, v55
	v_exp_f32_e32 v79, v32
	v_sub_f32_e32 v32, v46, v65
	v_exp_f32_e32 v51, v51
	v_sub_f32_e32 v52, v52, v65
	v_exp_f32_e32 v53, v53
	v_sub_f32_e32 v54, v54, v65
	v_exp_f32_e32 v80, v32
	v_sub_f32_e32 v32, v47, v65
	v_sub_f32_e32 v64, v105, v65
	v_exp_f32_e32 v52, v52
	v_exp_f32_e32 v54, v54
	v_sub_f32_e32 v56, v56, v65
	v_sub_f32_e32 v57, v57, v65
	v_sub_f32_e32 v58, v58, v65
	v_sub_f32_e32 v59, v59, v65
	v_sub_f32_e32 v60, v60, v65
	v_sub_f32_e32 v61, v61, v65
	v_sub_f32_e32 v62, v62, v65
	v_sub_f32_e32 v63, v63, v65
	v_exp_f32_e32 v65, v32
	v_add_f32_e32 v32, 0, v48
	v_add_f32_e32 v32, v49, v32
	v_add_f32_e32 v44, v50, v32
	ds_read2_b64 v[32:35], v143 offset0:128 offset1:130
	v_exp_f32_e32 v64, v64
	v_cvt_pk_bf16_f32 v39, v54, v55
	v_cvt_pk_bf16_f32 v38, v52, v53
	v_cvt_pk_bf16_f32 v37, v50, v51
	v_cvt_pk_bf16_f32 v36, v48, v49
	ds_read2_b64 v[40:43], v142 offset0:128 offset1:130
	v_pk_mul_f32 v[30:31], v[30:31], v[64:65] op_sel_hi:[1,0]
	v_pk_mul_f32 v[28:29], v[28:29], v[64:65] op_sel_hi:[1,0]
	v_pk_mul_f32 v[26:27], v[26:27], v[64:65] op_sel_hi:[1,0]
	v_pk_mul_f32 v[24:25], v[24:25], v[64:65] op_sel_hi:[1,0]
	v_pk_mul_f32 v[22:23], v[22:23], v[64:65] op_sel_hi:[1,0]
	v_pk_mul_f32 v[20:21], v[20:21], v[64:65] op_sel_hi:[1,0]
	v_pk_mul_f32 v[18:19], v[18:19], v[64:65] op_sel_hi:[1,0]
	v_pk_mul_f32 v[16:17], v[16:17], v[64:65] op_sel_hi:[1,0]
	v_exp_f32_e32 v57, v57
	v_exp_f32_e32 v59, v59
	s_waitcnt lgkmcnt(1)
	v_mfma_f32_32x32x16_bf16 v[16:31], v[32:35], v[36:39], v[16:31]
	v_add_f32_e32 v32, v51, v44
	v_exp_f32_e32 v56, v56
	v_exp_f32_e32 v58, v58
	v_exp_f32_e32 v60, v60
	v_exp_f32_e32 v62, v62
	v_add_f32_e32 v32, v52, v32
	v_exp_f32_e32 v61, v61
	v_exp_f32_e32 v63, v63
	v_add_f32_e32 v32, v53, v32
	v_pk_mul_f32 v[14:15], v[14:15], v[64:65] op_sel_hi:[1,0]
	v_pk_mul_f32 v[12:13], v[12:13], v[64:65] op_sel_hi:[1,0]
	v_pk_mul_f32 v[10:11], v[10:11], v[64:65] op_sel_hi:[1,0]
	v_pk_mul_f32 v[8:9], v[8:9], v[64:65] op_sel_hi:[1,0]
	v_pk_mul_f32 v[6:7], v[6:7], v[64:65] op_sel_hi:[1,0]
	v_pk_mul_f32 v[4:5], v[4:5], v[64:65] op_sel_hi:[1,0]
	v_pk_mul_f32 v[2:3], v[2:3], v[64:65] op_sel_hi:[1,0]
	v_pk_mul_f32 v[0:1], v[0:1], v[64:65] op_sel_hi:[1,0]
	v_add_f32_e32 v32, v54, v32
	v_add_f32_e32 v48, v55, v32
	s_waitcnt lgkmcnt(0)
	v_mfma_f32_32x32x16_bf16 v[0:15], v[40:43], v[36:39], v[0:15]
	ds_read2_b64 v[32:35], v143 offset0:132 offset1:134
	ds_read2_b64 v[44:47], v142 offset0:132 offset1:134
	v_add_f32_e32 v40, v56, v48
	v_cvt_pk_bf16_f32 v39, v62, v63
	v_cvt_pk_bf16_f32 v38, v60, v61
	v_cvt_pk_bf16_f32 v37, v58, v59
	v_cvt_pk_bf16_f32 v36, v56, v57
	s_waitcnt lgkmcnt(1)
	s_nop 0
	v_mfma_f32_32x32x16_bf16 v[16:31], v[32:35], v[36:39], v[16:31]
	v_add_f32_e32 v32, v57, v40
	v_add_f32_e32 v32, v58, v32
	v_add_f32_e32 v32, v59, v32
	v_add_f32_e32 v32, v60, v32
	v_add_f32_e32 v32, v61, v32
	v_add_f32_e32 v32, v62, v32
	v_add_f32_e32 v32, v63, v32
	s_waitcnt lgkmcnt(0)
	v_mfma_f32_32x32x16_bf16 v[0:15], v[44:47], v[36:39], v[0:15]
	v_add_f32_e32 v44, v66, v32
	ds_read2_b64 v[32:35], v143 offset0:136 offset1:138
	v_cvt_pk_bf16_f32 v39, v72, v73
	v_cvt_pk_bf16_f32 v38, v70, v71
	v_cvt_pk_bf16_f32 v37, v68, v69
	v_cvt_pk_bf16_f32 v36, v66, v67
	ds_read2_b64 v[40:43], v142 offset0:136 offset1:138
	s_waitcnt lgkmcnt(1)
	v_mfma_f32_32x32x16_bf16 v[16:31], v[32:35], v[36:39], v[16:31]
	v_add_f32_e32 v32, v67, v44
	v_add_f32_e32 v32, v68, v32
	v_add_f32_e32 v32, v69, v32
	v_add_f32_e32 v32, v70, v32
	v_add_f32_e32 v32, v71, v32
	v_add_f32_e32 v32, v72, v32
	v_add_f32_e32 v32, v73, v32
	v_add_f32_e32 v32, v74, v32
	v_add_f32_e32 v32, v75, v32
	v_add_f32_e32 v32, v76, v32
	v_add_f32_e32 v32, v77, v32
	v_add_f32_e32 v32, v78, v32
	v_add_f32_e32 v32, v79, v32
	v_add_f32_e32 v32, v80, v32
	s_waitcnt lgkmcnt(0)
	v_mfma_f32_32x32x16_bf16 v[0:15], v[40:43], v[36:39], v[0:15]
	v_add_f32_e32 v40, v65, v32
	ds_read2_b64 v[32:35], v141 offset0:140 offset1:142
	v_fmac_f32_e32 v40, v104, v64
	v_cvt_pk_bf16_f32 v39, v80, v65
	ds_bpermute_b32 v41, v123, v40
	v_cvt_pk_bf16_f32 v38, v78, v79
	v_cvt_pk_bf16_f32 v37, v76, v77
	v_cvt_pk_bf16_f32 v36, v74, v75
	v_mov_b32_e32 v123, v117
	s_waitcnt lgkmcnt(0)
	v_add_f32_e32 v40, v40, v41
	v_mfma_f32_32x32x16_bf16 v[16:31], v[32:35], v[36:39], v[16:31]
	ds_read2_b64 v[32:35], v140 offset0:140 offset1:142
	v_div_scale_f32 v41, s[0:1], v40, v40, 1.0
	v_rcp_f32_e32 v42, v41
	s_waitcnt lgkmcnt(0)
	v_mfma_f32_32x32x16_bf16 v[0:15], v[32:35], v[36:39], v[0:15]
	v_fma_f32 v32, -v41, v42, 1.0
	v_fmac_f32_e32 v42, v32, v42
	v_div_scale_f32 v32, vcc, 1.0, v40, 1.0
	v_mul_f32_e32 v33, v32, v42
	v_fma_f32 v34, -v41, v33, v32
	v_fmac_f32_e32 v33, v34, v42
	v_fma_f32 v32, -v41, v33, v32
	v_div_fmas_f32 v32, v32, v42, v33
	v_div_fixup_f32 v32, v32, v40, 1.0
	v_mov_b32_e32 v38, v16
	v_mov_b32_e32 v39, v18
	v_mov_b32_e32 v18, v17
	v_lshlrev_b64 v[34:35], 11, v[118:119]
	v_pk_mul_f32 v[38:39], v[38:39], v[32:33] op_sel_hi:[1,0]
	v_pk_mul_f32 v[16:17], v[18:19], v[32:33] op_sel_hi:[1,0]
	v_lshl_add_u64 v[34:35], s[8:9], 0, v[34:35]
	v_and_b32_sdwa v19, v38, v159 dst_sel:DWORD dst_unused:UNUSED_PAD src0_sel:WORD_1 src1_sel:DWORD
	v_and_b32_sdwa v33, v17, v159 dst_sel:DWORD dst_unused:UNUSED_PAD src0_sel:WORD_1 src1_sel:DWORD
	v_lshl_add_u64 v[34:35], v[120:121], 1, v[34:35]
	v_and_b32_sdwa v18, v39, v159 dst_sel:DWORD dst_unused:UNUSED_PAD src0_sel:WORD_1 src1_sel:DWORD
	v_add3_u32 v19, v38, v19, s59
	v_and_b32_sdwa v38, v16, v159 dst_sel:DWORD dst_unused:UNUSED_PAD src0_sel:WORD_1 src1_sel:DWORD
	v_add3_u32 v17, v17, v33, s59
	v_lshl_add_u64 v[34:35], v[34:35], 0, v[122:123]
	v_add3_u32 v18, v39, v18, s59
	v_add3_u32 v16, v16, v38, s59
	v_and_b32_e32 v17, 0xffff0000, v17
	v_and_b32_e32 v16, 0xffff0000, v16
	v_or_b32_sdwa v17, v17, v18 dst_sel:DWORD dst_unused:UNUSED_PAD src0_sel:DWORD src1_sel:WORD_1
	v_add_co_u32_e32 v18, vcc, s61, v34
	v_or_b32_sdwa v16, v16, v19 dst_sel:DWORD dst_unused:UNUSED_PAD src0_sel:DWORD src1_sel:WORD_1
	s_nop 0
	v_addc_co_u32_e32 v19, vcc, 0, v35, vcc
	global_store_dwordx2 v[18:19], v[16:17], off offset:3840
	v_mov_b32_e32 v16, v20
	v_mov_b32_e32 v17, v22
	v_pk_mul_f32 v[16:17], v[16:17], v[32:33] op_sel_hi:[1,0]
	v_mov_b32_e32 v22, v21
	v_pk_mul_f32 v[18:19], v[22:23], v[32:33] op_sel_hi:[1,0]
	v_and_b32_sdwa v20, v17, v159 dst_sel:DWORD dst_unused:UNUSED_PAD src0_sel:WORD_1 src1_sel:DWORD
	v_and_b32_sdwa v21, v16, v159 dst_sel:DWORD dst_unused:UNUSED_PAD src0_sel:WORD_1 src1_sel:DWORD
	v_add3_u32 v16, v16, v21, s59
	v_add3_u32 v17, v17, v20, s59
	v_and_b32_sdwa v20, v19, v159 dst_sel:DWORD dst_unused:UNUSED_PAD src0_sel:WORD_1 src1_sel:DWORD
	v_and_b32_sdwa v21, v18, v159 dst_sel:DWORD dst_unused:UNUSED_PAD src0_sel:WORD_1 src1_sel:DWORD
	v_add3_u32 v19, v19, v20, s59
	v_add3_u32 v18, v18, v21, s59
	v_and_b32_e32 v19, 0xffff0000, v19
	v_and_b32_e32 v18, 0xffff0000, v18
	v_lshl_add_u64 v[36:37], v[34:35], 0, s[48:49]
	v_or_b32_sdwa v17, v19, v17 dst_sel:DWORD dst_unused:UNUSED_PAD src0_sel:DWORD src1_sel:WORD_1
	v_or_b32_sdwa v16, v18, v16 dst_sel:DWORD dst_unused:UNUSED_PAD src0_sel:DWORD src1_sel:WORD_1
	global_store_dwordx2 v[36:37], v[16:17], off offset:16
	v_mov_b32_e32 v16, v24
	v_mov_b32_e32 v17, v26
	v_pk_mul_f32 v[16:17], v[16:17], v[32:33] op_sel_hi:[1,0]
	v_mov_b32_e32 v26, v25
	v_pk_mul_f32 v[18:19], v[26:27], v[32:33] op_sel_hi:[1,0]
	v_and_b32_sdwa v20, v17, v159 dst_sel:DWORD dst_unused:UNUSED_PAD src0_sel:WORD_1 src1_sel:DWORD
	v_and_b32_sdwa v21, v16, v159 dst_sel:DWORD dst_unused:UNUSED_PAD src0_sel:WORD_1 src1_sel:DWORD
	v_add3_u32 v16, v16, v21, s59
	v_add3_u32 v17, v17, v20, s59
	v_and_b32_sdwa v20, v19, v159 dst_sel:DWORD dst_unused:UNUSED_PAD src0_sel:WORD_1 src1_sel:DWORD
	v_and_b32_sdwa v21, v18, v159 dst_sel:DWORD dst_unused:UNUSED_PAD src0_sel:WORD_1 src1_sel:DWORD
	v_add3_u32 v19, v19, v20, s59
	v_add3_u32 v18, v18, v21, s59
	v_and_b32_e32 v19, 0xffff0000, v19
	v_and_b32_e32 v18, 0xffff0000, v18
	v_or_b32_sdwa v17, v19, v17 dst_sel:DWORD dst_unused:UNUSED_PAD src0_sel:DWORD src1_sel:WORD_1
	v_or_b32_sdwa v16, v18, v16 dst_sel:DWORD dst_unused:UNUSED_PAD src0_sel:DWORD src1_sel:WORD_1
	global_store_dwordx2 v[36:37], v[16:17], off offset:32
	v_mov_b32_e32 v16, v28
	v_mov_b32_e32 v17, v30
	v_pk_mul_f32 v[16:17], v[16:17], v[32:33] op_sel_hi:[1,0]
	v_mov_b32_e32 v30, v29
	v_pk_mul_f32 v[18:19], v[30:31], v[32:33] op_sel_hi:[1,0]
	v_and_b32_sdwa v20, v17, v159 dst_sel:DWORD dst_unused:UNUSED_PAD src0_sel:WORD_1 src1_sel:DWORD
	v_and_b32_sdwa v21, v16, v159 dst_sel:DWORD dst_unused:UNUSED_PAD src0_sel:WORD_1 src1_sel:DWORD
	v_add3_u32 v16, v16, v21, s59
	v_add3_u32 v17, v17, v20, s59
	v_and_b32_sdwa v20, v19, v159 dst_sel:DWORD dst_unused:UNUSED_PAD src0_sel:WORD_1 src1_sel:DWORD
	v_and_b32_sdwa v21, v18, v159 dst_sel:DWORD dst_unused:UNUSED_PAD src0_sel:WORD_1 src1_sel:DWORD
	v_add3_u32 v19, v19, v20, s59
	v_add3_u32 v18, v18, v21, s59
	v_and_b32_e32 v19, 0xffff0000, v19
	v_and_b32_e32 v18, 0xffff0000, v18
	v_or_b32_sdwa v17, v19, v17 dst_sel:DWORD dst_unused:UNUSED_PAD src0_sel:DWORD src1_sel:WORD_1
	v_or_b32_sdwa v16, v18, v16 dst_sel:DWORD dst_unused:UNUSED_PAD src0_sel:DWORD src1_sel:WORD_1
	global_store_dwordx2 v[36:37], v[16:17], off offset:48
	v_mov_b32_e32 v16, v0
	v_mov_b32_e32 v17, v2
	v_pk_mul_f32 v[16:17], v[16:17], v[32:33] op_sel_hi:[1,0]
	v_mov_b32_e32 v2, v1
	v_pk_mul_f32 v[0:1], v[2:3], v[32:33] op_sel_hi:[1,0]
	v_and_b32_sdwa v2, v17, v159 dst_sel:DWORD dst_unused:UNUSED_PAD src0_sel:WORD_1 src1_sel:DWORD
	v_and_b32_sdwa v3, v16, v159 dst_sel:DWORD dst_unused:UNUSED_PAD src0_sel:WORD_1 src1_sel:DWORD
	v_add3_u32 v3, v16, v3, s59
	v_add3_u32 v2, v17, v2, s59
	v_and_b32_sdwa v16, v1, v159 dst_sel:DWORD dst_unused:UNUSED_PAD src0_sel:WORD_1 src1_sel:DWORD
	v_and_b32_sdwa v17, v0, v159 dst_sel:DWORD dst_unused:UNUSED_PAD src0_sel:WORD_1 src1_sel:DWORD
	v_add3_u32 v1, v1, v16, s59
	v_add3_u32 v0, v0, v17, s59
	v_and_b32_e32 v1, 0xffff0000, v1
	v_and_b32_e32 v0, 0xffff0000, v0
	v_or_b32_sdwa v1, v1, v2 dst_sel:DWORD dst_unused:UNUSED_PAD src0_sel:DWORD src1_sel:WORD_1
	v_or_b32_sdwa v0, v0, v3 dst_sel:DWORD dst_unused:UNUSED_PAD src0_sel:DWORD src1_sel:WORD_1
	global_store_dwordx2 v[36:37], v[0:1], off offset:64
	v_mov_b32_e32 v0, v4
	v_mov_b32_e32 v1, v6
	v_pk_mul_f32 v[0:1], v[0:1], v[32:33] op_sel_hi:[1,0]
	v_mov_b32_e32 v6, v5
	v_pk_mul_f32 v[2:3], v[6:7], v[32:33] op_sel_hi:[1,0]
	v_and_b32_sdwa v4, v1, v159 dst_sel:DWORD dst_unused:UNUSED_PAD src0_sel:WORD_1 src1_sel:DWORD
	v_and_b32_sdwa v5, v0, v159 dst_sel:DWORD dst_unused:UNUSED_PAD src0_sel:WORD_1 src1_sel:DWORD
	v_add3_u32 v0, v0, v5, s59
	v_add3_u32 v1, v1, v4, s59
	v_and_b32_sdwa v4, v3, v159 dst_sel:DWORD dst_unused:UNUSED_PAD src0_sel:WORD_1 src1_sel:DWORD
	v_and_b32_sdwa v5, v2, v159 dst_sel:DWORD dst_unused:UNUSED_PAD src0_sel:WORD_1 src1_sel:DWORD
	v_add3_u32 v3, v3, v4, s59
	v_add3_u32 v2, v2, v5, s59
	v_and_b32_e32 v3, 0xffff0000, v3
	v_and_b32_e32 v2, 0xffff0000, v2
	v_or_b32_sdwa v1, v3, v1 dst_sel:DWORD dst_unused:UNUSED_PAD src0_sel:DWORD src1_sel:WORD_1
	v_or_b32_sdwa v0, v2, v0 dst_sel:DWORD dst_unused:UNUSED_PAD src0_sel:DWORD src1_sel:WORD_1
	global_store_dwordx2 v[36:37], v[0:1], off offset:80
	v_mov_b32_e32 v0, v8
	v_mov_b32_e32 v1, v10
	v_pk_mul_f32 v[0:1], v[0:1], v[32:33] op_sel_hi:[1,0]
	v_mov_b32_e32 v10, v9
	v_pk_mul_f32 v[2:3], v[10:11], v[32:33] op_sel_hi:[1,0]
	v_and_b32_sdwa v4, v1, v159 dst_sel:DWORD dst_unused:UNUSED_PAD src0_sel:WORD_1 src1_sel:DWORD
	v_and_b32_sdwa v5, v0, v159 dst_sel:DWORD dst_unused:UNUSED_PAD src0_sel:WORD_1 src1_sel:DWORD
	v_add3_u32 v0, v0, v5, s59
	v_add3_u32 v1, v1, v4, s59
	v_and_b32_sdwa v4, v3, v159 dst_sel:DWORD dst_unused:UNUSED_PAD src0_sel:WORD_1 src1_sel:DWORD
	v_and_b32_sdwa v5, v2, v159 dst_sel:DWORD dst_unused:UNUSED_PAD src0_sel:WORD_1 src1_sel:DWORD
	v_add3_u32 v3, v3, v4, s59
	v_add3_u32 v2, v2, v5, s59
	v_and_b32_e32 v3, 0xffff0000, v3
	v_and_b32_e32 v2, 0xffff0000, v2
	v_or_b32_sdwa v1, v3, v1 dst_sel:DWORD dst_unused:UNUSED_PAD src0_sel:DWORD src1_sel:WORD_1
	v_or_b32_sdwa v0, v2, v0 dst_sel:DWORD dst_unused:UNUSED_PAD src0_sel:DWORD src1_sel:WORD_1
	global_store_dwordx2 v[36:37], v[0:1], off offset:96
	v_mov_b32_e32 v0, v12
	v_mov_b32_e32 v1, v14
	v_pk_mul_f32 v[0:1], v[0:1], v[32:33] op_sel_hi:[1,0]
	v_mov_b32_e32 v14, v13
	v_pk_mul_f32 v[2:3], v[14:15], v[32:33] op_sel_hi:[1,0]
	v_and_b32_sdwa v4, v1, v159 dst_sel:DWORD dst_unused:UNUSED_PAD src0_sel:WORD_1 src1_sel:DWORD
	v_and_b32_sdwa v5, v0, v159 dst_sel:DWORD dst_unused:UNUSED_PAD src0_sel:WORD_1 src1_sel:DWORD
	v_add3_u32 v0, v0, v5, s59
	v_add3_u32 v1, v1, v4, s59
	v_and_b32_sdwa v4, v3, v159 dst_sel:DWORD dst_unused:UNUSED_PAD src0_sel:WORD_1 src1_sel:DWORD
	v_and_b32_sdwa v5, v2, v159 dst_sel:DWORD dst_unused:UNUSED_PAD src0_sel:WORD_1 src1_sel:DWORD
	v_add3_u32 v3, v3, v4, s59
	v_add3_u32 v2, v2, v5, s59
	v_and_b32_e32 v3, 0xffff0000, v3
	v_and_b32_e32 v2, 0xffff0000, v2
	v_or_b32_sdwa v1, v3, v1 dst_sel:DWORD dst_unused:UNUSED_PAD src0_sel:DWORD src1_sel:WORD_1
	v_or_b32_sdwa v0, v2, v0 dst_sel:DWORD dst_unused:UNUSED_PAD src0_sel:DWORD src1_sel:WORD_1
	global_store_dwordx2 v[36:37], v[0:1], off offset:112
	s_branch .LBB0_579

.LBB0_1684:
	s_waitcnt lgkmcnt(0)
	s_barrier
	s_waitcnt vmcnt(0)
	ds_write_b128 v161, v[224:227]
	ds_write_b128 v162, v[228:231]
	ds_write_b128 v163, v[232:235]
	ds_write_b128 v164, v[236:239] offset:13312
	ds_write_b128 v165, v[240:243] offset:13312
	s_waitcnt lgkmcnt(0)
	s_barrier
	ds_read_b128 v[32:35], v116
	ds_read_b128 v[88:91], v116 offset:32
	v_lshl_add_u64 v[100:101], s[8:9], 0, v[138:139]
	v_lshl_add_u64 v[144:145], s[8:9], 0, v[136:137]
	v_lshl_add_u64 v[102:103], s[8:9], 0, v[134:135]
	v_lshl_add_u64 v[106:107], s[8:9], 0, v[132:133]
	v_lshl_add_u64 v[104:105], s[8:9], 0, v[130:131]
	v_lshl_add_u64 v[140:141], s[8:9], 0, v[128:129]
	v_lshl_add_u64 v[142:143], s[8:9], 0, v[126:127]
	v_lshl_add_u64 v[146:147], s[8:9], 0, v[124:125]
	v_cndmask_b32_e32 v97, v145, v101, vcc
	v_cndmask_b32_e32 v96, v144, v100, vcc
	v_cndmask_b32_e64 v99, v107, v103, s[4:5]
	v_cndmask_b32_e64 v98, v106, v102, s[4:5]
	v_cndmask_b32_e64 v145, v141, v105, s[6:7]
	v_cndmask_b32_e64 v144, v140, v104, s[6:7]
	global_load_dwordx4 v[236:239], v[142:143], off
	global_load_dwordx4 v[240:243], v[146:147], off
	global_load_dwordx4 v[224:227], v[96:97], off
	global_load_dwordx4 v[228:231], v[98:99], off
	global_load_dwordx4 v[232:235], v[144:145], off
	s_waitcnt lgkmcnt(1)
	v_mfma_f32_32x32x16_bf16 v[32:47], v[32:35], v[84:87], 0
	ds_read_b128 v[48:51], v116 offset:6656
	ds_read_b128 v[92:95], v116 offset:6688
	v_mov_b32_e32 v167, v109
	v_mov_b32_e32 v166, v108
	s_waitcnt lgkmcnt(1)
	v_mfma_f32_32x32x16_bf16 v[48:63], v[48:51], v[84:87], 0
	v_add_u32_e32 v172, v122, v159
	v_add_u32_e32 v173, v122, v160
	s_add_i32 s0, s0, -1
	v_mfma_f32_32x32x16_bf16 v[32:47], v[88:91], v[80:83], v[32:47]
	ds_read_b128 v[88:91], v116 offset:64
	v_lshl_add_u64 v[124:125], v[124:125], 0, s[44:45]
	v_lshl_add_u64 v[126:127], v[126:127], 0, s[44:45]
	v_lshl_add_u64 v[128:129], v[128:129], 0, s[46:47]
	v_lshl_add_u64 v[130:131], v[130:131], 0, s[48:49]
	v_lshl_add_u64 v[132:133], v[132:133], 0, s[46:47]
	v_lshl_add_u64 v[134:135], v[134:135], 0, s[48:49]
	s_waitcnt lgkmcnt(1)
	v_mfma_f32_32x32x16_bf16 v[48:63], v[92:95], v[80:83], v[48:63]
	ds_read_b128 v[168:171], v116 offset:96
	ds_read_b128 v[92:95], v116 offset:6720
	ds_read_b128 v[96:99], v116 offset:6752
	v_lshl_add_u64 v[136:137], v[136:137], 0, s[46:47]
	v_lshl_add_u64 v[138:139], v[138:139], 0, s[48:49]
	s_cmp_lg_u32 s0, 0
	s_waitcnt lgkmcnt(3)
	v_mfma_f32_32x32x16_bf16 v[32:47], v[88:91], v[76:79], v[32:47]
	s_waitcnt lgkmcnt(1)
	v_mfma_f32_32x32x16_bf16 v[48:63], v[92:95], v[76:79], v[48:63]
	ds_read_b128 v[92:95], v116 offset:128
	ds_read_b128 v[112:115], v116 offset:160
	ds_read_b128 v[88:91], v116 offset:6784
	ds_read_b128 v[108:111], v116 offset:6816
	v_mfma_f32_32x32x16_bf16 v[32:47], v[168:171], v[72:75], v[32:47]
	v_add_u32_e32 v168, v158, v159
	v_add_u32_e32 v169, v158, v160
	s_waitcnt lgkmcnt(4)
	v_mfma_f32_32x32x16_bf16 v[48:63], v[96:99], v[72:75], v[48:63]
	s_waitcnt lgkmcnt(0)
	v_mfma_f32_32x32x16_bf16 v[32:47], v[92:95], v[68:71], v[32:47]
	v_add_u32_e32 v143, 0x3000, v172
	v_add_u32_e32 v142, 0x3000, v173
	v_add_u32_e32 v141, 0x3000, v168
	v_add_u32_e32 v140, 0x3000, v169
	v_mfma_f32_32x32x16_bf16 v[48:63], v[88:91], v[68:71], v[48:63]
	s_nop 0
	ds_read2_b64 v[144:147], v143 offset0:128 offset1:130
	v_mfma_f32_32x32x16_bf16 v[32:47], v[112:115], v[64:67], v[32:47]
	ds_read2_b64 v[112:115], v143 offset0:132 offset1:134
	ds_read2_b64 v[168:171], v142 offset0:128 offset1:130
	ds_read2_b64 v[172:175], v142 offset0:132 offset1:134
	ds_read2_b64 v[176:179], v143 offset0:136 offset1:138
	ds_read2_b64 v[180:183], v142 offset0:136 offset1:138
	ds_read2_b64 v[184:187], v141 offset0:140 offset1:142
	ds_read2_b64 v[188:191], v140 offset0:140 offset1:142
	v_mfma_f32_32x32x16_bf16 v[48:63], v[108:111], v[64:67], v[48:63]
	s_nop 3
	v_max_f32_e32 v108, v33, v33
	v_max_f32_e32 v109, v32, v32
	v_max_f32_e32 v108, v109, v108
	v_max3_f32 v108, v108, v34, v35
	v_max3_f32 v108, v108, v36, v37
	v_max3_f32 v108, v108, v38, v39
	v_max3_f32 v108, v108, v40, v41
	v_max3_f32 v108, v108, v42, v43
	v_max3_f32 v108, v108, v44, v45
	v_max3_f32 v108, v108, v46, v47
	v_max3_f32 v108, v108, v48, v49
	v_max3_f32 v108, v108, v50, v51
	v_max3_f32 v108, v108, v52, v53
	v_max3_f32 v108, v108, v54, v55
	v_max3_f32 v108, v108, v56, v57
	v_max3_f32 v108, v108, v58, v59
	v_max3_f32 v108, v108, v60, v61
	v_max3_f32 v108, v108, v62, v63
	ds_bpermute_b32 v109, v123, v108
	s_waitcnt lgkmcnt(0)
	v_max3_f32 v109, v167, v108, v109
	v_sub_f32_e32 v108, v167, v109
	v_sub_f32_e32 v32, v32, v109
	v_sub_f32_e32 v33, v33, v109
	v_sub_f32_e32 v34, v34, v109
	v_sub_f32_e32 v35, v35, v109
	v_sub_f32_e32 v36, v36, v109
	v_sub_f32_e32 v37, v37, v109
	v_sub_f32_e32 v38, v38, v109
	v_sub_f32_e32 v39, v39, v109
	v_sub_f32_e32 v110, v42, v109
	v_exp_f32_e32 v42, v108
	v_exp_f32_e32 v32, v32
	v_exp_f32_e32 v33, v33
	s_nop 0
	v_cvt_pk_bf16_f32 v244, v32, v33
	v_exp_f32_e32 v108, v34
	v_exp_f32_e32 v111, v35
	v_exp_f32_e32 v167, v36
	v_exp_f32_e32 v192, v37
	v_exp_f32_e32 v193, v38
	v_exp_f32_e32 v194, v39
	v_sub_f32_e32 v43, v43, v109
	v_sub_f32_e32 v40, v40, v109
	v_sub_f32_e32 v41, v41, v109
	v_exp_f32_e32 v43, v43
	v_exp_f32_e32 v195, v40
	v_exp_f32_e32 v196, v41
	v_add_f32_e32 v34, 0, v32
	v_add_f32_e32 v222, v33, v34
	v_sub_f32_e32 v44, v44, v109
	v_sub_f32_e32 v45, v45, v109
	v_sub_f32_e32 v46, v46, v109
	v_pk_mul_f32 v[30:31], v[30:31], v[42:43] op_sel_hi:[1,0]
	v_pk_mul_f32 v[28:29], v[28:29], v[42:43] op_sel_hi:[1,0]
	v_pk_mul_f32 v[26:27], v[26:27], v[42:43] op_sel_hi:[1,0]
	v_pk_mul_f32 v[24:25], v[24:25], v[42:43] op_sel_hi:[1,0]
	v_pk_mul_f32 v[22:23], v[22:23], v[42:43] op_sel_hi:[1,0]
	v_pk_mul_f32 v[20:21], v[20:21], v[42:43] op_sel_hi:[1,0]
	v_pk_mul_f32 v[18:19], v[18:19], v[42:43] op_sel_hi:[1,0]
	v_pk_mul_f32 v[16:17], v[16:17], v[42:43] op_sel_hi:[1,0]
	v_pk_mul_f32 v[14:15], v[14:15], v[42:43] op_sel_hi:[1,0]
	v_pk_mul_f32 v[12:13], v[12:13], v[42:43] op_sel_hi:[1,0]
	v_pk_mul_f32 v[10:11], v[10:11], v[42:43] op_sel_hi:[1,0]
	v_pk_mul_f32 v[8:9], v[8:9], v[42:43] op_sel_hi:[1,0]
	v_pk_mul_f32 v[6:7], v[6:7], v[42:43] op_sel_hi:[1,0]
	v_pk_mul_f32 v[4:5], v[4:5], v[42:43] op_sel_hi:[1,0]
	v_pk_mul_f32 v[2:3], v[2:3], v[42:43] op_sel_hi:[1,0]
	v_pk_mul_f32 v[0:1], v[0:1], v[42:43] op_sel_hi:[1,0]
	v_cvt_pk_bf16_f32 v35, v193, v194
	v_cvt_pk_bf16_f32 v34, v167, v192
	v_cvt_pk_bf16_f32 v33, v108, v111
	v_mov_b32_e32 v32, v244
	v_sub_f32_e32 v47, v47, v109
	v_exp_f32_e32 v110, v110
	v_exp_f32_e32 v44, v44
	v_exp_f32_e32 v45, v45
	v_exp_f32_e32 v46, v46
	v_mfma_f32_32x32x16_bf16 v[16:31], v[144:147], v[32:35], v[16:31]
	v_exp_f32_e32 v47, v47
	v_mfma_f32_32x32x16_bf16 v[0:15], v[168:171], v[32:35], v[0:15]
	v_add_f32_e32 v37, v108, v222
	v_cvt_pk_bf16_f32 v35, v46, v47
	v_cvt_pk_bf16_f32 v34, v44, v45
	v_cvt_pk_bf16_f32 v33, v110, v43
	v_cvt_pk_bf16_f32 v32, v195, v196
	v_add_f32_e32 v108, v111, v37
	v_sub_f32_e32 v48, v48, v109
	v_mfma_f32_32x32x16_bf16 v[16:31], v[112:115], v[32:35], v[16:31]
	v_sub_f32_e32 v49, v49, v109
	v_sub_f32_e32 v50, v50, v109
	v_sub_f32_e32 v51, v51, v109
	v_sub_f32_e32 v52, v52, v109
	v_sub_f32_e32 v53, v53, v109
	v_sub_f32_e32 v54, v54, v109
	v_sub_f32_e32 v55, v55, v109
	v_mfma_f32_32x32x16_bf16 v[0:15], v[172:175], v[32:35], v[0:15]
	v_add_f32_e32 v32, v167, v108
	v_add_f32_e32 v32, v192, v32
	v_add_f32_e32 v32, v193, v32
	v_add_f32_e32 v32, v194, v32
	v_add_f32_e32 v32, v195, v32
	v_sub_f32_e32 v56, v56, v109
	v_exp_f32_e32 v48, v48
	v_exp_f32_e32 v49, v49
	v_exp_f32_e32 v50, v50
	v_exp_f32_e32 v51, v51
	v_exp_f32_e32 v52, v52
	v_exp_f32_e32 v53, v53
	v_exp_f32_e32 v54, v54
	v_add_f32_e32 v32, v196, v32
	v_exp_f32_e32 v55, v55
	v_exp_f32_e32 v56, v56
	v_add_f32_e32 v32, v110, v32
	v_add_f32_e32 v32, v43, v32
	v_add_f32_e32 v32, v44, v32
	v_add_f32_e32 v32, v45, v32
	v_add_f32_e32 v32, v46, v32
	v_add_f32_e32 v32, v47, v32
	v_sub_f32_e32 v57, v57, v109
	v_sub_f32_e32 v58, v58, v109
	v_sub_f32_e32 v59, v59, v109
	v_sub_f32_e32 v60, v60, v109
	v_sub_f32_e32 v61, v61, v109
	v_sub_f32_e32 v62, v62, v109
	v_cvt_pk_bf16_f32 v37, v54, v55
	v_cvt_pk_bf16_f32 v36, v52, v53
	v_cvt_pk_bf16_f32 v35, v50, v51
	v_cvt_pk_bf16_f32 v34, v48, v49
	v_add_f32_e32 v32, v48, v32
	v_sub_f32_e32 v63, v63, v109
	v_exp_f32_e32 v57, v57
	v_exp_f32_e32 v58, v58
	v_exp_f32_e32 v59, v59
	v_exp_f32_e32 v60, v60
	v_exp_f32_e32 v61, v61
	v_exp_f32_e32 v62, v62
	v_mfma_f32_32x32x16_bf16 v[16:31], v[176:179], v[34:37], v[16:31]
	v_add_f32_e32 v32, v49, v32
	v_exp_f32_e32 v63, v63
	v_add_f32_e32 v32, v50, v32
	v_add_f32_e32 v32, v51, v32
	v_add_f32_e32 v32, v52, v32
	v_mfma_f32_32x32x16_bf16 v[0:15], v[180:183], v[34:37], v[0:15]
	v_add_f32_e32 v32, v53, v32
	v_add_f32_e32 v32, v54, v32
	v_add_f32_e32 v32, v55, v32
	v_cvt_pk_bf16_f32 v41, v62, v63
	v_cvt_pk_bf16_f32 v40, v60, v61
	v_cvt_pk_bf16_f32 v39, v58, v59
	v_cvt_pk_bf16_f32 v38, v56, v57
	v_add_f32_e32 v32, v56, v32
	v_add_f32_e32 v32, v57, v32
	v_mfma_f32_32x32x16_bf16 v[16:31], v[184:187], v[38:41], v[16:31]
	v_add_f32_e32 v32, v58, v32
	v_add_f32_e32 v32, v59, v32
	v_add_f32_e32 v32, v60, v32
	v_add_f32_e32 v32, v61, v32
	v_add_f32_e32 v32, v62, v32
	v_add_f32_e32 v108, v63, v32
	v_fmac_f32_e32 v108, v166, v42
	v_mfma_f32_32x32x16_bf16 v[0:15], v[188:191], v[38:41], v[0:15]
	s_cbranch_scc1 .LBB0_1684
	s_barrier
	s_waitcnt vmcnt(0)
	ds_write_b128 v161, v[224:227]
	ds_write_b128 v162, v[228:231]
	ds_write_b128 v163, v[232:235]
	ds_write_b128 v164, v[236:239] offset:13312
	ds_write_b128 v165, v[240:243] offset:13312
	s_waitcnt lgkmcnt(0)
	s_barrier
	ds_read_b128 v[32:35], v116
	ds_read_b128 v[36:39], v116 offset:32
	s_waitcnt lgkmcnt(1)
	v_mfma_f32_32x32x16_bf16 v[48:63], v[32:35], v[84:87], 0
	s_waitcnt lgkmcnt(0)
	v_mfma_f32_32x32x16_bf16 v[48:63], v[36:39], v[80:83], v[48:63]
	ds_read_b128 v[32:35], v116 offset:64
	ds_read_b128 v[36:39], v116 offset:96
	s_waitcnt lgkmcnt(1)
	v_mfma_f32_32x32x16_bf16 v[48:63], v[32:35], v[76:79], v[48:63]
	s_waitcnt lgkmcnt(0)
	v_mfma_f32_32x32x16_bf16 v[48:63], v[36:39], v[72:75], v[48:63]
	ds_read_b128 v[32:35], v116 offset:128
	ds_read_b128 v[36:39], v116 offset:160
	s_waitcnt lgkmcnt(1)
	v_mfma_f32_32x32x16_bf16 v[48:63], v[32:35], v[68:71], v[48:63]
	ds_read_b128 v[32:35], v116 offset:6656
	ds_read_b128 v[88:91], v116 offset:6688
	s_waitcnt lgkmcnt(2)
	v_mfma_f32_32x32x16_bf16 v[48:63], v[36:39], v[64:67], v[48:63]
	s_waitcnt lgkmcnt(1)
	v_mfma_f32_32x32x16_bf16 v[32:47], v[32:35], v[84:87], 0
	s_waitcnt lgkmcnt(0)
	v_mfma_f32_32x32x16_bf16 v[32:47], v[88:91], v[80:83], v[32:47]
	ds_read_b128 v[80:83], v116 offset:6720
	ds_read_b128 v[84:87], v116 offset:6752
	s_waitcnt lgkmcnt(1)
	v_mfma_f32_32x32x16_bf16 v[32:47], v[80:83], v[76:79], v[32:47]
	s_nop 3
	v_max_f32_e32 v80, v49, v49
	v_max_f32_e32 v81, v48, v48
	v_max_f32_e32 v80, v81, v80
	s_waitcnt lgkmcnt(0)
	v_mfma_f32_32x32x16_bf16 v[32:47], v[84:87], v[72:75], v[32:47]
	ds_read_b128 v[72:75], v116 offset:6784
	ds_read_b128 v[76:79], v116 offset:6816
	s_waitcnt lgkmcnt(1)
	v_mfma_f32_32x32x16_bf16 v[32:47], v[72:75], v[68:71], v[32:47]
	v_max3_f32 v68, v80, v50, v51
	v_max3_f32 v68, v68, v52, v53
	v_max3_f32 v68, v68, v54, v55
	v_max3_f32 v68, v68, v56, v57
	v_max3_f32 v68, v68, v58, v59
	v_max3_f32 v68, v68, v60, v61
	v_max3_f32 v68, v68, v62, v63
	s_waitcnt lgkmcnt(0)
	v_mfma_f32_32x32x16_bf16 v[32:47], v[76:79], v[64:67], v[32:47]
	s_nop 11
	v_max3_f32 v64, v68, v32, v33
	v_max3_f32 v64, v64, v34, v35
	v_max3_f32 v64, v64, v36, v37
	v_max3_f32 v64, v64, v38, v39
	v_max3_f32 v64, v64, v40, v41
	v_max3_f32 v64, v64, v42, v43
	v_max3_f32 v64, v64, v44, v45
	v_max3_f32 v64, v64, v46, v47
	ds_bpermute_b32 v65, v123, v64
	s_waitcnt lgkmcnt(0)
	v_max3_f32 v65, v109, v64, v65
	v_sub_f32_e32 v32, v32, v65
	v_exp_f32_e32 v66, v32
	v_sub_f32_e32 v32, v33, v65
	v_exp_f32_e32 v67, v32
	v_sub_f32_e32 v32, v34, v65
	v_exp_f32_e32 v68, v32
	v_sub_f32_e32 v32, v35, v65
	v_exp_f32_e32 v69, v32
	v_sub_f32_e32 v32, v36, v65
	v_exp_f32_e32 v70, v32
	v_sub_f32_e32 v32, v37, v65
	v_exp_f32_e32 v71, v32
	v_sub_f32_e32 v32, v38, v65
	v_exp_f32_e32 v72, v32
	v_sub_f32_e32 v32, v39, v65
	v_exp_f32_e32 v73, v32
	v_sub_f32_e32 v32, v40, v65
	v_exp_f32_e32 v74, v32
	v_sub_f32_e32 v32, v41, v65
	v_exp_f32_e32 v75, v32
	v_sub_f32_e32 v32, v42, v65
	v_sub_f32_e32 v48, v48, v65
	v_exp_f32_e32 v76, v32
	v_sub_f32_e32 v32, v43, v65
	v_exp_f32_e32 v48, v48
	v_sub_f32_e32 v49, v49, v65
	v_exp_f32_e32 v77, v32
	v_sub_f32_e32 v32, v44, v65
	v_exp_f32_e32 v49, v49
	v_sub_f32_e32 v50, v50, v65
	v_sub_f32_e32 v55, v55, v65
	v_exp_f32_e32 v78, v32
	v_sub_f32_e32 v32, v45, v65
	v_exp_f32_e32 v50, v50
	v_sub_f32_e32 v51, v51, v65
	v_sub_f32_e32 v53, v53, v65
	v_exp_f32_e32 v55, v55
	v_exp_f32_e32 v79, v32
	v_sub_f32_e32 v32, v46, v65
	v_exp_f32_e32 v51, v51
	v_sub_f32_e32 v52, v52, v65
	v_exp_f32_e32 v53, v53
	v_sub_f32_e32 v54, v54, v65
	v_exp_f32_e32 v80, v32
	v_sub_f32_e32 v32, v47, v65
	v_sub_f32_e32 v64, v109, v65
	v_exp_f32_e32 v52, v52
	v_exp_f32_e32 v54, v54
	v_sub_f32_e32 v56, v56, v65
	v_sub_f32_e32 v57, v57, v65
	v_sub_f32_e32 v58, v58, v65
	v_sub_f32_e32 v59, v59, v65
	v_sub_f32_e32 v60, v60, v65
	v_sub_f32_e32 v61, v61, v65
	v_sub_f32_e32 v62, v62, v65
	v_sub_f32_e32 v63, v63, v65
	v_exp_f32_e32 v65, v32
	v_add_f32_e32 v32, 0, v48
	v_add_f32_e32 v32, v49, v32
	v_add_f32_e32 v44, v50, v32
	ds_read2_b64 v[32:35], v143 offset0:128 offset1:130
	v_exp_f32_e32 v64, v64
	v_cvt_pk_bf16_f32 v39, v54, v55
	v_cvt_pk_bf16_f32 v38, v52, v53
	v_cvt_pk_bf16_f32 v37, v50, v51
	v_cvt_pk_bf16_f32 v36, v48, v49
	ds_read2_b64 v[40:43], v142 offset0:128 offset1:130
	v_pk_mul_f32 v[30:31], v[30:31], v[64:65] op_sel_hi:[1,0]
	v_pk_mul_f32 v[28:29], v[28:29], v[64:65] op_sel_hi:[1,0]
	v_pk_mul_f32 v[26:27], v[26:27], v[64:65] op_sel_hi:[1,0]
	v_pk_mul_f32 v[24:25], v[24:25], v[64:65] op_sel_hi:[1,0]
	v_pk_mul_f32 v[22:23], v[22:23], v[64:65] op_sel_hi:[1,0]
	v_pk_mul_f32 v[20:21], v[20:21], v[64:65] op_sel_hi:[1,0]
	v_pk_mul_f32 v[18:19], v[18:19], v[64:65] op_sel_hi:[1,0]
	v_pk_mul_f32 v[16:17], v[16:17], v[64:65] op_sel_hi:[1,0]
	v_exp_f32_e32 v57, v57
	v_exp_f32_e32 v59, v59
	s_waitcnt lgkmcnt(1)
	v_mfma_f32_32x32x16_bf16 v[16:31], v[32:35], v[36:39], v[16:31]
	v_add_f32_e32 v32, v51, v44
	v_exp_f32_e32 v56, v56
	v_exp_f32_e32 v58, v58
	v_exp_f32_e32 v60, v60
	v_exp_f32_e32 v62, v62
	v_add_f32_e32 v32, v52, v32
	v_exp_f32_e32 v61, v61
	v_exp_f32_e32 v63, v63
	v_add_f32_e32 v32, v53, v32
	v_pk_mul_f32 v[14:15], v[14:15], v[64:65] op_sel_hi:[1,0]
	v_pk_mul_f32 v[12:13], v[12:13], v[64:65] op_sel_hi:[1,0]
	v_pk_mul_f32 v[10:11], v[10:11], v[64:65] op_sel_hi:[1,0]
	v_pk_mul_f32 v[8:9], v[8:9], v[64:65] op_sel_hi:[1,0]
	v_pk_mul_f32 v[6:7], v[6:7], v[64:65] op_sel_hi:[1,0]
	v_pk_mul_f32 v[4:5], v[4:5], v[64:65] op_sel_hi:[1,0]
	v_pk_mul_f32 v[2:3], v[2:3], v[64:65] op_sel_hi:[1,0]
	v_pk_mul_f32 v[0:1], v[0:1], v[64:65] op_sel_hi:[1,0]
	v_add_f32_e32 v32, v54, v32
	v_add_f32_e32 v48, v55, v32
	s_waitcnt lgkmcnt(0)
	v_mfma_f32_32x32x16_bf16 v[0:15], v[40:43], v[36:39], v[0:15]
	ds_read2_b64 v[32:35], v143 offset0:132 offset1:134
	ds_read2_b64 v[44:47], v142 offset0:132 offset1:134
	v_add_f32_e32 v40, v56, v48
	v_cvt_pk_bf16_f32 v39, v62, v63
	v_cvt_pk_bf16_f32 v38, v60, v61
	v_cvt_pk_bf16_f32 v37, v58, v59
	v_cvt_pk_bf16_f32 v36, v56, v57
	s_waitcnt lgkmcnt(1)
	s_nop 0
	v_mfma_f32_32x32x16_bf16 v[16:31], v[32:35], v[36:39], v[16:31]
	v_add_f32_e32 v32, v57, v40
	v_add_f32_e32 v32, v58, v32
	v_add_f32_e32 v32, v59, v32
	v_add_f32_e32 v32, v60, v32
	v_add_f32_e32 v32, v61, v32
	v_add_f32_e32 v32, v62, v32
	v_add_f32_e32 v32, v63, v32
	s_waitcnt lgkmcnt(0)
	v_mfma_f32_32x32x16_bf16 v[0:15], v[44:47], v[36:39], v[0:15]
	v_add_f32_e32 v44, v66, v32
	ds_read2_b64 v[32:35], v143 offset0:136 offset1:138
	v_cvt_pk_bf16_f32 v39, v72, v73
	v_cvt_pk_bf16_f32 v38, v70, v71
	v_cvt_pk_bf16_f32 v37, v68, v69
	v_cvt_pk_bf16_f32 v36, v66, v67
	ds_read2_b64 v[40:43], v142 offset0:136 offset1:138
	s_waitcnt lgkmcnt(1)
	v_mfma_f32_32x32x16_bf16 v[16:31], v[32:35], v[36:39], v[16:31]
	v_add_f32_e32 v32, v67, v44
	v_add_f32_e32 v32, v68, v32
	v_add_f32_e32 v32, v69, v32
	v_add_f32_e32 v32, v70, v32
	v_add_f32_e32 v32, v71, v32
	v_add_f32_e32 v32, v72, v32
	v_add_f32_e32 v32, v73, v32
	v_add_f32_e32 v32, v74, v32
	v_add_f32_e32 v32, v75, v32
	v_add_f32_e32 v32, v76, v32
	v_add_f32_e32 v32, v77, v32
	v_add_f32_e32 v32, v78, v32
	v_add_f32_e32 v32, v79, v32
	v_add_f32_e32 v32, v80, v32
	s_waitcnt lgkmcnt(0)
	v_mfma_f32_32x32x16_bf16 v[0:15], v[40:43], v[36:39], v[0:15]
	v_add_f32_e32 v40, v65, v32
	ds_read2_b64 v[32:35], v141 offset0:140 offset1:142
	v_fmac_f32_e32 v40, v108, v64
	v_cvt_pk_bf16_f32 v39, v80, v65
	ds_bpermute_b32 v41, v123, v40
	v_cvt_pk_bf16_f32 v38, v78, v79
	v_cvt_pk_bf16_f32 v37, v76, v77
	v_cvt_pk_bf16_f32 v36, v74, v75
	v_mov_b32_e32 v123, v117
	s_waitcnt lgkmcnt(0)
	v_add_f32_e32 v40, v40, v41
	v_mfma_f32_32x32x16_bf16 v[16:31], v[32:35], v[36:39], v[16:31]
	ds_read2_b64 v[32:35], v140 offset0:140 offset1:142
	v_div_scale_f32 v41, s[0:1], v40, v40, 1.0
	v_rcp_f32_e32 v42, v41
	s_waitcnt lgkmcnt(0)
	v_mfma_f32_32x32x16_bf16 v[0:15], v[32:35], v[36:39], v[0:15]
	v_fma_f32 v32, -v41, v42, 1.0
	v_fmac_f32_e32 v42, v32, v42
	v_div_scale_f32 v32, vcc, 1.0, v40, 1.0
	v_mul_f32_e32 v33, v32, v42
	v_fma_f32 v34, -v41, v33, v32
	v_fmac_f32_e32 v33, v34, v42
	v_fma_f32 v32, -v41, v33, v32
	v_div_fmas_f32 v32, v32, v42, v33
	v_div_fixup_f32 v32, v32, v40, 1.0
	v_mov_b32_e32 v38, v16
	v_mov_b32_e32 v39, v18
	v_mov_b32_e32 v18, v17
	v_lshlrev_b64 v[34:35], 11, v[118:119]
	v_pk_mul_f32 v[38:39], v[38:39], v[32:33] op_sel_hi:[1,0]
	v_pk_mul_f32 v[16:17], v[18:19], v[32:33] op_sel_hi:[1,0]
	v_lshl_add_u64 v[34:35], s[8:9], 0, v[34:35]
	v_and_b32_sdwa v19, v38, v155 dst_sel:DWORD dst_unused:UNUSED_PAD src0_sel:WORD_1 src1_sel:DWORD
	v_and_b32_sdwa v33, v17, v155 dst_sel:DWORD dst_unused:UNUSED_PAD src0_sel:WORD_1 src1_sel:DWORD
	v_lshl_add_u64 v[34:35], v[120:121], 1, v[34:35]
	v_and_b32_sdwa v18, v39, v155 dst_sel:DWORD dst_unused:UNUSED_PAD src0_sel:WORD_1 src1_sel:DWORD
	v_add3_u32 v19, v38, v19, s61
	v_and_b32_sdwa v38, v16, v155 dst_sel:DWORD dst_unused:UNUSED_PAD src0_sel:WORD_1 src1_sel:DWORD
	v_add3_u32 v17, v17, v33, s61
	v_lshl_add_u64 v[34:35], v[34:35], 0, v[122:123]
	v_add3_u32 v18, v39, v18, s61
	v_add3_u32 v16, v16, v38, s61
	v_and_b32_e32 v17, 0xffff0000, v17
	v_and_b32_e32 v16, 0xffff0000, v16
	v_or_b32_sdwa v17, v17, v18 dst_sel:DWORD dst_unused:UNUSED_PAD src0_sel:DWORD src1_sel:WORD_1
	v_add_co_u32_e32 v18, vcc, s63, v34
	v_or_b32_sdwa v16, v16, v19 dst_sel:DWORD dst_unused:UNUSED_PAD src0_sel:DWORD src1_sel:WORD_1
	s_nop 0
	v_addc_co_u32_e32 v19, vcc, 0, v35, vcc
	global_store_dwordx2 v[18:19], v[16:17], off offset:3840
	v_mov_b32_e32 v16, v20
	v_mov_b32_e32 v17, v22
	v_pk_mul_f32 v[16:17], v[16:17], v[32:33] op_sel_hi:[1,0]
	v_mov_b32_e32 v22, v21
	v_pk_mul_f32 v[18:19], v[22:23], v[32:33] op_sel_hi:[1,0]
	v_and_b32_sdwa v20, v17, v155 dst_sel:DWORD dst_unused:UNUSED_PAD src0_sel:WORD_1 src1_sel:DWORD
	v_and_b32_sdwa v21, v16, v155 dst_sel:DWORD dst_unused:UNUSED_PAD src0_sel:WORD_1 src1_sel:DWORD
	v_add3_u32 v16, v16, v21, s61
	v_add3_u32 v17, v17, v20, s61
	v_and_b32_sdwa v20, v19, v155 dst_sel:DWORD dst_unused:UNUSED_PAD src0_sel:WORD_1 src1_sel:DWORD
	v_and_b32_sdwa v21, v18, v155 dst_sel:DWORD dst_unused:UNUSED_PAD src0_sel:WORD_1 src1_sel:DWORD
	v_add3_u32 v19, v19, v20, s61
	v_add3_u32 v18, v18, v21, s61
	v_and_b32_e32 v19, 0xffff0000, v19
	v_and_b32_e32 v18, 0xffff0000, v18
	v_lshl_add_u64 v[36:37], v[34:35], 0, s[50:51]
	v_or_b32_sdwa v17, v19, v17 dst_sel:DWORD dst_unused:UNUSED_PAD src0_sel:DWORD src1_sel:WORD_1
	v_or_b32_sdwa v16, v18, v16 dst_sel:DWORD dst_unused:UNUSED_PAD src0_sel:DWORD src1_sel:WORD_1
	global_store_dwordx2 v[36:37], v[16:17], off offset:16
	v_mov_b32_e32 v16, v24
	v_mov_b32_e32 v17, v26
	v_pk_mul_f32 v[16:17], v[16:17], v[32:33] op_sel_hi:[1,0]
	v_mov_b32_e32 v26, v25
	v_pk_mul_f32 v[18:19], v[26:27], v[32:33] op_sel_hi:[1,0]
	v_and_b32_sdwa v20, v17, v155 dst_sel:DWORD dst_unused:UNUSED_PAD src0_sel:WORD_1 src1_sel:DWORD
	v_and_b32_sdwa v21, v16, v155 dst_sel:DWORD dst_unused:UNUSED_PAD src0_sel:WORD_1 src1_sel:DWORD
	v_add3_u32 v16, v16, v21, s61
	v_add3_u32 v17, v17, v20, s61
	v_and_b32_sdwa v20, v19, v155 dst_sel:DWORD dst_unused:UNUSED_PAD src0_sel:WORD_1 src1_sel:DWORD
	v_and_b32_sdwa v21, v18, v155 dst_sel:DWORD dst_unused:UNUSED_PAD src0_sel:WORD_1 src1_sel:DWORD
	v_add3_u32 v19, v19, v20, s61
	v_add3_u32 v18, v18, v21, s61
	v_and_b32_e32 v19, 0xffff0000, v19
	v_and_b32_e32 v18, 0xffff0000, v18
	v_or_b32_sdwa v17, v19, v17 dst_sel:DWORD dst_unused:UNUSED_PAD src0_sel:DWORD src1_sel:WORD_1
	v_or_b32_sdwa v16, v18, v16 dst_sel:DWORD dst_unused:UNUSED_PAD src0_sel:DWORD src1_sel:WORD_1
	global_store_dwordx2 v[36:37], v[16:17], off offset:32
	v_mov_b32_e32 v16, v28
	v_mov_b32_e32 v17, v30
	v_pk_mul_f32 v[16:17], v[16:17], v[32:33] op_sel_hi:[1,0]
	v_mov_b32_e32 v30, v29
	v_pk_mul_f32 v[18:19], v[30:31], v[32:33] op_sel_hi:[1,0]
	v_and_b32_sdwa v20, v17, v155 dst_sel:DWORD dst_unused:UNUSED_PAD src0_sel:WORD_1 src1_sel:DWORD
	v_and_b32_sdwa v21, v16, v155 dst_sel:DWORD dst_unused:UNUSED_PAD src0_sel:WORD_1 src1_sel:DWORD
	v_add3_u32 v16, v16, v21, s61
	v_add3_u32 v17, v17, v20, s61
	v_and_b32_sdwa v20, v19, v155 dst_sel:DWORD dst_unused:UNUSED_PAD src0_sel:WORD_1 src1_sel:DWORD
	v_and_b32_sdwa v21, v18, v155 dst_sel:DWORD dst_unused:UNUSED_PAD src0_sel:WORD_1 src1_sel:DWORD
	v_add3_u32 v19, v19, v20, s61
	v_add3_u32 v18, v18, v21, s61
	v_and_b32_e32 v19, 0xffff0000, v19
	v_and_b32_e32 v18, 0xffff0000, v18
	v_or_b32_sdwa v17, v19, v17 dst_sel:DWORD dst_unused:UNUSED_PAD src0_sel:DWORD src1_sel:WORD_1
	v_or_b32_sdwa v16, v18, v16 dst_sel:DWORD dst_unused:UNUSED_PAD src0_sel:DWORD src1_sel:WORD_1
	global_store_dwordx2 v[36:37], v[16:17], off offset:48
	v_mov_b32_e32 v16, v0
	v_mov_b32_e32 v17, v2
	v_pk_mul_f32 v[16:17], v[16:17], v[32:33] op_sel_hi:[1,0]
	v_mov_b32_e32 v2, v1
	v_pk_mul_f32 v[0:1], v[2:3], v[32:33] op_sel_hi:[1,0]
	v_and_b32_sdwa v2, v17, v155 dst_sel:DWORD dst_unused:UNUSED_PAD src0_sel:WORD_1 src1_sel:DWORD
	v_and_b32_sdwa v3, v16, v155 dst_sel:DWORD dst_unused:UNUSED_PAD src0_sel:WORD_1 src1_sel:DWORD
	v_add3_u32 v3, v16, v3, s61
	v_add3_u32 v2, v17, v2, s61
	v_and_b32_sdwa v16, v1, v155 dst_sel:DWORD dst_unused:UNUSED_PAD src0_sel:WORD_1 src1_sel:DWORD
	v_and_b32_sdwa v17, v0, v155 dst_sel:DWORD dst_unused:UNUSED_PAD src0_sel:WORD_1 src1_sel:DWORD
	v_add3_u32 v1, v1, v16, s61
	v_add3_u32 v0, v0, v17, s61
	v_and_b32_e32 v1, 0xffff0000, v1
	v_and_b32_e32 v0, 0xffff0000, v0
	v_or_b32_sdwa v1, v1, v2 dst_sel:DWORD dst_unused:UNUSED_PAD src0_sel:DWORD src1_sel:WORD_1
	v_or_b32_sdwa v0, v0, v3 dst_sel:DWORD dst_unused:UNUSED_PAD src0_sel:DWORD src1_sel:WORD_1
	global_store_dwordx2 v[36:37], v[0:1], off offset:64
	v_mov_b32_e32 v0, v4
	v_mov_b32_e32 v1, v6
	v_pk_mul_f32 v[0:1], v[0:1], v[32:33] op_sel_hi:[1,0]
	v_mov_b32_e32 v6, v5
	v_pk_mul_f32 v[2:3], v[6:7], v[32:33] op_sel_hi:[1,0]
	v_and_b32_sdwa v4, v1, v155 dst_sel:DWORD dst_unused:UNUSED_PAD src0_sel:WORD_1 src1_sel:DWORD
	v_and_b32_sdwa v5, v0, v155 dst_sel:DWORD dst_unused:UNUSED_PAD src0_sel:WORD_1 src1_sel:DWORD
	v_add3_u32 v0, v0, v5, s61
	v_add3_u32 v1, v1, v4, s61
	v_and_b32_sdwa v4, v3, v155 dst_sel:DWORD dst_unused:UNUSED_PAD src0_sel:WORD_1 src1_sel:DWORD
	v_and_b32_sdwa v5, v2, v155 dst_sel:DWORD dst_unused:UNUSED_PAD src0_sel:WORD_1 src1_sel:DWORD
	v_add3_u32 v3, v3, v4, s61
	v_add3_u32 v2, v2, v5, s61
	v_and_b32_e32 v3, 0xffff0000, v3
	v_and_b32_e32 v2, 0xffff0000, v2
	v_or_b32_sdwa v1, v3, v1 dst_sel:DWORD dst_unused:UNUSED_PAD src0_sel:DWORD src1_sel:WORD_1
	v_or_b32_sdwa v0, v2, v0 dst_sel:DWORD dst_unused:UNUSED_PAD src0_sel:DWORD src1_sel:WORD_1
	global_store_dwordx2 v[36:37], v[0:1], off offset:80
	v_mov_b32_e32 v0, v8
	v_mov_b32_e32 v1, v10
	v_pk_mul_f32 v[0:1], v[0:1], v[32:33] op_sel_hi:[1,0]
	v_mov_b32_e32 v10, v9
	v_pk_mul_f32 v[2:3], v[10:11], v[32:33] op_sel_hi:[1,0]
	v_and_b32_sdwa v4, v1, v155 dst_sel:DWORD dst_unused:UNUSED_PAD src0_sel:WORD_1 src1_sel:DWORD
	v_and_b32_sdwa v5, v0, v155 dst_sel:DWORD dst_unused:UNUSED_PAD src0_sel:WORD_1 src1_sel:DWORD
	v_add3_u32 v0, v0, v5, s61
	v_add3_u32 v1, v1, v4, s61
	v_and_b32_sdwa v4, v3, v155 dst_sel:DWORD dst_unused:UNUSED_PAD src0_sel:WORD_1 src1_sel:DWORD
	v_and_b32_sdwa v5, v2, v155 dst_sel:DWORD dst_unused:UNUSED_PAD src0_sel:WORD_1 src1_sel:DWORD
	v_add3_u32 v3, v3, v4, s61
	v_add3_u32 v2, v2, v5, s61
	v_and_b32_e32 v3, 0xffff0000, v3
	v_and_b32_e32 v2, 0xffff0000, v2
	v_or_b32_sdwa v1, v3, v1 dst_sel:DWORD dst_unused:UNUSED_PAD src0_sel:DWORD src1_sel:WORD_1
	v_or_b32_sdwa v0, v2, v0 dst_sel:DWORD dst_unused:UNUSED_PAD src0_sel:DWORD src1_sel:WORD_1
	global_store_dwordx2 v[36:37], v[0:1], off offset:96
	v_mov_b32_e32 v0, v12
	v_mov_b32_e32 v1, v14
	v_pk_mul_f32 v[0:1], v[0:1], v[32:33] op_sel_hi:[1,0]
	v_mov_b32_e32 v14, v13
	v_pk_mul_f32 v[2:3], v[14:15], v[32:33] op_sel_hi:[1,0]
	v_and_b32_sdwa v4, v1, v155 dst_sel:DWORD dst_unused:UNUSED_PAD src0_sel:WORD_1 src1_sel:DWORD
	v_and_b32_sdwa v5, v0, v155 dst_sel:DWORD dst_unused:UNUSED_PAD src0_sel:WORD_1 src1_sel:DWORD
	v_add3_u32 v0, v0, v5, s61
	v_add3_u32 v1, v1, v4, s61
	v_and_b32_sdwa v4, v3, v155 dst_sel:DWORD dst_unused:UNUSED_PAD src0_sel:WORD_1 src1_sel:DWORD
	v_and_b32_sdwa v5, v2, v155 dst_sel:DWORD dst_unused:UNUSED_PAD src0_sel:WORD_1 src1_sel:DWORD
	v_add3_u32 v3, v3, v4, s61
	v_add3_u32 v2, v2, v5, s61
	v_and_b32_e32 v3, 0xffff0000, v3
	v_and_b32_e32 v2, 0xffff0000, v2
	v_or_b32_sdwa v1, v3, v1 dst_sel:DWORD dst_unused:UNUSED_PAD src0_sel:DWORD src1_sel:WORD_1
	v_or_b32_sdwa v0, v2, v0 dst_sel:DWORD dst_unused:UNUSED_PAD src0_sel:DWORD src1_sel:WORD_1
	global_store_dwordx2 v[36:37], v[0:1], off offset:112
	s_branch .LBB0_1562
